# baseline (speedup 1.0000x reference)
; __device__ __forceinline__ float sigm_f(float x) { return __builtin_amdgcn_rcpf(1.f + __builtin_amdgcn_exp2f(x * -1.4426950408889634f)); }
; __device__ __forceinline__ float silu_f(float x) { return x * sigm_f(x); }
; #define SCHED __builtin_amdgcn_sched_barrier(0)
; template <int ACT>
; __device__ __forceinline__ void epi_tok(f32x4 (&acc)[2][2][4][2], bf16* __restrict__ dst, int ld, int tok0, int colbase,
;                                         const float* __restrict__ bias, float scale) {
;   TC t = get_tc();
;   const int odd = t.fq & 1;
;   const int paddr = ((t.fq ^ 1) * 16 + t.fr) << 2;
;   _Pragma("unroll") for (int ai = 0; ai < 2; ++ai) _Pragma("unroll") for (int bj = 0; bj < 2; ++bj) _Pragma("unroll") for (int m = 0; m < 4; ++m) {
;     uint2 pk[2];
;     _Pragma("unroll") for (int n = 0; n < 2; ++n) {
;       f32x4 v = acc[ai][bj][m][n];
;       if (ACT == 0) { _Pragma("unroll") for (int j = 0; j < 4; ++j) v[j] = silu_f(v[j]); }
;       else if (ACT == 1) { float4 b = *(const float4*)(bias + colbase + bj * 128 + t.wc * 32 + n * 16 + t.fq * 4);
;         v[0] = sigm_f(v[0] + b.x); v[1] = sigm_f(v[1] + b.y); v[2] = sigm_f(v[2] + b.z); v[3] = sigm_f(v[3] + b.w); }
;       else { _Pragma("unroll") for (int j = 0; j < 4; ++j) v[j] *= scale; }
;       pk[n] = pack4(v[0], v[1], v[2], v[3]);
;     }
;     const uint2 snd = odd ? pk[0] : pk[1];
;     uint2 rcv;
;     rcv.x = (unsigned)__builtin_amdgcn_ds_bpermute(paddr, (int)snd.x);
;     rcv.y = (unsigned)__builtin_amdgcn_ds_bpermute(paddr, (int)snd.y);
;     const u32x4 outv = odd ? u32x4{rcv.x, rcv.y, pk[1].x, pk[1].y} : u32x4{pk[0].x, pk[0].y, rcv.x, rcv.y};
;     const int row = ai * 128 + t.wr * 64 + m * 16 + t.fr;
;     const int col = bj * 128 + t.wc * 32 + (odd ? 16 + (t.fq - 1) * 4 : t.fq * 4);
;     *(u32x4*)(dst + (size_t)(tok0 + row) * ld + colbase + col) = outv;
;     SCHED;
;   }
; }
; __device__ __forceinline__ void phase_inproj(const Params& p, const Grp& g, int l) {
;     ...
;       bf16* dst = (ci < 2) ? SZF : SZA;
;       const int ld = (ci < 2) ? 512 : 1024, colbase = (ci < 2) ? ci * 256 : (ci - 2) * 256;
;       epi_tok<0>(acc, dst, ld, tok0, colbase, nullptr, 1.f);
.LBB0_508:
	s_and_b64 s[8:9], s[0:1], exec
	s_mov_b32 s7, 0x13260000
	s_cselect_b32 s7, s7, 0x23260000
	s_add_u32 s10, s58, s7
	v_mov_b32_e32 v128, v190
	s_addc_u32 s11, s59, 0
	s_lshl_b32 s7, s40, 8
	s_add_i32 s12, s7, 0xfffffe00
	v_lshlrev_b32_e32 v129, 2, v128
	v_lshrrev_b32_e32 v133, 2, v128
	v_bitop3_b32 v130, v129, 64, v194 bitop3:0x6c
	v_and_b32_e32 v129, 16, v128
	v_ashrrev_i32_e32 v131, 2, v128
	v_and_b32_e32 v133, 12, v133
	s_and_b64 s[8:9], s[0:1], exec
	v_and_b32_e32 v131, 0xffffffc0, v131
	v_lshrrev_b32_e32 v132, 1, v128
	v_add_u32_e32 v134, 12, v133
	v_cmp_eq_u32_e32 vcc, 0, v129
	v_and_or_b32 v128, v128, 15, s6
	s_cselect_b32 s8, s7, s12
	v_cndmask_b32_e32 v129, v134, v133, vcc
	s_movk_i32 s7, 0x60
	v_add_u32_e32 v128, v128, v131
	v_mul_f32_e32 v131, 0xbfb8aa3b, v124
	v_and_or_b32 v129, v132, s7, v129
	v_exp_f32_e32 v131, v131
	v_mul_f32_e32 v132, 0xbfb8aa3b, v125
	v_exp_f32_e32 v133, v132
	v_mul_f32_e32 v134, 0xbfb8aa3b, v127
	v_add_f32_e32 v131, 1.0, v131
	v_rcp_f32_e32 v132, v131
	v_add_f32_e32 v131, 1.0, v133
	v_rcp_f32_e32 v133, v131
	v_mul_f32_e32 v131, 0xbfb8aa3b, v126
	v_exp_f32_e32 v131, v131
	v_exp_f32_e32 v134, v134
	v_pk_mul_f32 v[124:125], v[124:125], v[132:133]
	s_ashr_i32 s9, s8, 31
	v_add_f32_e32 v131, 1.0, v131
	v_rcp_f32_e32 v132, v131
	v_add_f32_e32 v131, 1.0, v134
	v_rcp_f32_e32 v133, v131
	v_mul_f32_e32 v131, 0xbfb8aa3b, v120
	v_exp_f32_e32 v131, v131
	v_mul_f32_e32 v134, 0xbfb8aa3b, v121
	v_exp_f32_e32 v134, v134
	v_pk_mul_f32 v[126:127], v[126:127], v[132:133]
	v_add_f32_e32 v131, 1.0, v131
	v_mul_f32_e32 v133, 0xbfb8aa3b, v122
	v_rcp_f32_e32 v132, v131
	v_add_f32_e32 v131, 1.0, v134
	v_exp_f32_e32 v134, v133
	v_mul_f32_e32 v133, 0xbfb8aa3b, v123
	v_exp_f32_e32 v135, v133
	v_rcp_f32_e32 v133, v131
	v_add_f32_e32 v131, 1.0, v134
	v_rcp_f32_e32 v134, v131
	v_add_f32_e32 v131, 1.0, v135
	v_rcp_f32_e32 v135, v131
	v_cvt_pk_bf16_f32 v124, v124, v125
	v_cvt_pk_bf16_f32 v125, v126, v127
	v_pk_mul_f32 v[120:121], v[120:121], v[132:133]
	v_pk_mul_f32 v[122:123], v[122:123], v[134:135]
	v_cvt_pk_bf16_f32 v126, v120, v121
	v_cvt_pk_bf16_f32 v122, v122, v123
	s_lshl_b64 s[6:7], s[8:9], 1
	s_add_u32 s6, s10, s6
	s_addc_u32 s7, s11, s7
	s_and_b64 s[0:1], s[0:1], exec
	v_lshlrev_b32_e32 v186, 1, v129
	v_ashrrev_i32_e32 v129, 31, v128
	s_cselect_b32 s0, 9, 10
	v_lshl_add_u64 v[120:121], s[6:7], 0, v[186:187]
	s_waitcnt lgkmcnt(0)
	s_nop 1
	v_permlane16_swap_b32 v125, v122
	v_permlane16_swap_b32 v124, v126
	v_mov_b32_e32 v127, v122
	v_lshlrev_b64 v[122:123], s0, v[128:129]
	v_lshl_add_u64 v[122:123], v[122:123], 1, v[120:121]
	global_store_dwordx4 v[122:123], v[124:127], off
	s_nop 1
	v_mul_f32_e32 v124, 0xbfb8aa3b, v116
	v_mul_f32_e32 v125, 0xbfb8aa3b, v117
	v_exp_f32_e32 v124, v124
	v_exp_f32_e32 v125, v125
	v_add_f32_e32 v124, 1.0, v124
	v_add_f32_e32 v125, 1.0, v125
	v_rcp_f32_e32 v124, v124
	v_rcp_f32_e32 v125, v125
	s_nop 0
	v_pk_mul_f32 v[116:117], v[116:117], v[124:125]
	v_mul_f32_e32 v124, 0xbfb8aa3b, v118
	v_mul_f32_e32 v125, 0xbfb8aa3b, v119
	v_exp_f32_e32 v124, v124
	v_exp_f32_e32 v125, v125
	v_add_f32_e32 v124, 1.0, v124
	v_add_f32_e32 v125, 1.0, v125
	v_rcp_f32_e32 v124, v124
	v_rcp_f32_e32 v125, v125
	s_nop 0
	v_pk_mul_f32 v[118:119], v[118:119], v[124:125]
	v_cvt_pk_bf16_f32 v124, v116, v117
	v_mul_f32_e32 v116, 0xbfb8aa3b, v112
	v_mul_f32_e32 v117, 0xbfb8aa3b, v113
	v_exp_f32_e32 v116, v116
	v_exp_f32_e32 v117, v117
	v_cvt_pk_bf16_f32 v118, v118, v119
	v_add_f32_e32 v116, 1.0, v116
	v_add_f32_e32 v117, 1.0, v117
	v_rcp_f32_e32 v116, v116
	v_rcp_f32_e32 v117, v117
	s_nop 0
	v_pk_mul_f32 v[112:113], v[112:113], v[116:117]
	v_mul_f32_e32 v116, 0xbfb8aa3b, v114
	v_mul_f32_e32 v117, 0xbfb8aa3b, v115
	v_exp_f32_e32 v116, v116
	v_exp_f32_e32 v117, v117
	v_cvt_pk_bf16_f32 v112, v112, v113
	v_add_f32_e32 v116, 1.0, v116
	v_add_f32_e32 v117, 1.0, v117
	v_rcp_f32_e32 v116, v116
	v_rcp_f32_e32 v117, v117
	s_nop 0
	v_pk_mul_f32 v[114:115], v[114:115], v[116:117]
	s_nop 0
	v_cvt_pk_bf16_f32 v113, v114, v115
	s_waitcnt lgkmcnt(0)
	s_nop 1
	v_permlane16_swap_b32 v124, v112
	v_permlane16_swap_b32 v118, v113
	v_mov_b32_e32 v114, v124
	v_mov_b32_e32 v116, v112
	v_mov_b32_e32 v115, v118
	v_mov_b32_e32 v117, v113
	v_or_b32_e32 v112, 16, v128
	v_ashrrev_i32_e32 v113, 31, v112
	v_lshlrev_b64 v[112:113], s0, v[112:113]
	v_lshl_add_u64 v[112:113], v[112:113], 1, v[120:121]
	global_store_dwordx4 v[112:113], v[114:117], off
	s_nop 1
	v_mul_f32_e32 v114, 0xbfb8aa3b, v108
	v_mul_f32_e32 v115, 0xbfb8aa3b, v109
	v_exp_f32_e32 v114, v114
	v_exp_f32_e32 v115, v115
	v_add_f32_e32 v114, 1.0, v114
	v_add_f32_e32 v115, 1.0, v115
	v_rcp_f32_e32 v114, v114
	v_rcp_f32_e32 v115, v115
	s_nop 0
	v_pk_mul_f32 v[108:109], v[108:109], v[114:115]
	v_mul_f32_e32 v114, 0xbfb8aa3b, v110
	v_mul_f32_e32 v115, 0xbfb8aa3b, v111
	v_exp_f32_e32 v114, v114
	v_exp_f32_e32 v115, v115
	v_add_f32_e32 v114, 1.0, v114
	v_add_f32_e32 v115, 1.0, v115
	v_rcp_f32_e32 v114, v114
	v_rcp_f32_e32 v115, v115
	s_nop 0
	v_pk_mul_f32 v[110:111], v[110:111], v[114:115]
	v_cvt_pk_bf16_f32 v114, v108, v109
	v_mul_f32_e32 v108, 0xbfb8aa3b, v104
	v_mul_f32_e32 v109, 0xbfb8aa3b, v105
	v_exp_f32_e32 v108, v108
	v_exp_f32_e32 v109, v109
	v_cvt_pk_bf16_f32 v110, v110, v111
	v_add_f32_e32 v108, 1.0, v108
	v_add_f32_e32 v109, 1.0, v109
	v_rcp_f32_e32 v108, v108
	v_rcp_f32_e32 v109, v109
	s_nop 0
	v_pk_mul_f32 v[104:105], v[104:105], v[108:109]
	v_mul_f32_e32 v108, 0xbfb8aa3b, v106
	v_mul_f32_e32 v109, 0xbfb8aa3b, v107
	v_exp_f32_e32 v108, v108
	v_exp_f32_e32 v109, v109
	v_cvt_pk_bf16_f32 v104, v104, v105
	v_add_f32_e32 v108, 1.0, v108
	v_add_f32_e32 v109, 1.0, v109
	v_rcp_f32_e32 v108, v108
	v_rcp_f32_e32 v109, v109
	s_nop 0
	v_pk_mul_f32 v[106:107], v[106:107], v[108:109]
	s_nop 0
	v_cvt_pk_bf16_f32 v105, v106, v107
	s_waitcnt lgkmcnt(0)
; __device__ __forceinline__ float sigm_f(float x) { return __builtin_amdgcn_rcpf(1.f + __builtin_amdgcn_exp2f(x * -1.4426950408889634f)); }
; __device__ __forceinline__ float silu_f(float x) { return x * sigm_f(x); }
; #define SCHED __builtin_amdgcn_sched_barrier(0)
; template <int ACT>
; __device__ __forceinline__ void epi_tok(f32x4 (&acc)[2][2][4][2], bf16* __restrict__ dst, int ld, int tok0, int colbase,
;                                         const float* __restrict__ bias, float scale) {
;     ...
;   _Pragma("unroll") for (int ai = 0; ai < 2; ++ai) _Pragma("unroll") for (int bj = 0; bj < 2; ++bj) _Pragma("unroll") for (int m = 0; m < 4; ++m) {
;     uint2 pk[2];
;     _Pragma("unroll") for (int n = 0; n < 2; ++n) {
;       f32x4 v = acc[ai][bj][m][n];
;       if (ACT == 0) { _Pragma("unroll") for (int j = 0; j < 4; ++j) v[j] = silu_f(v[j]); }
;       else if (ACT == 1) { float4 b = *(const float4*)(bias + colbase + bj * 128 + t.wc * 32 + n * 16 + t.fq * 4);
;         v[0] = sigm_f(v[0] + b.x); v[1] = sigm_f(v[1] + b.y); v[2] = sigm_f(v[2] + b.z); v[3] = sigm_f(v[3] + b.w); }
;       else { _Pragma("unroll") for (int j = 0; j < 4; ++j) v[j] *= scale; }
;       pk[n] = pack4(v[0], v[1], v[2], v[3]);
;     }
;     const uint2 snd = odd ? pk[0] : pk[1];
;     uint2 rcv;
;     rcv.x = (unsigned)__builtin_amdgcn_ds_bpermute(paddr, (int)snd.x);
;     rcv.y = (unsigned)__builtin_amdgcn_ds_bpermute(paddr, (int)snd.y);
;     const u32x4 outv = odd ? u32x4{rcv.x, rcv.y, pk[1].x, pk[1].y} : u32x4{pk[0].x, pk[0].y, rcv.x, rcv.y};
;     const int row = ai * 128 + t.wr * 64 + m * 16 + t.fr;
;     const int col = bj * 128 + t.wc * 32 + (odd ? 16 + (t.fq - 1) * 4 : t.fq * 4);
;     *(u32x4*)(dst + (size_t)(tok0 + row) * ld + colbase + col) = outv;
;     SCHED;
;   }
	s_nop 1
	v_permlane16_swap_b32 v114, v104
	v_permlane16_swap_b32 v110, v105
	v_mov_b32_e32 v106, v114
	v_mov_b32_e32 v108, v104
	v_mov_b32_e32 v107, v110
	v_mov_b32_e32 v109, v105
	v_or_b32_e32 v104, 32, v128
	v_ashrrev_i32_e32 v105, 31, v104
	v_lshlrev_b64 v[104:105], s0, v[104:105]
	v_lshl_add_u64 v[104:105], v[104:105], 1, v[120:121]
	global_store_dwordx4 v[104:105], v[106:109], off
	s_nop 1
	v_mul_f32_e32 v106, 0xbfb8aa3b, v100
	v_mul_f32_e32 v107, 0xbfb8aa3b, v101
	v_exp_f32_e32 v106, v106
	v_exp_f32_e32 v107, v107
	v_add_f32_e32 v106, 1.0, v106
	v_add_f32_e32 v107, 1.0, v107
	v_rcp_f32_e32 v106, v106
	v_rcp_f32_e32 v107, v107
	s_nop 0
	v_pk_mul_f32 v[100:101], v[100:101], v[106:107]
	v_mul_f32_e32 v106, 0xbfb8aa3b, v102
	v_mul_f32_e32 v107, 0xbfb8aa3b, v103
	v_exp_f32_e32 v106, v106
	v_exp_f32_e32 v107, v107
	v_add_f32_e32 v106, 1.0, v106
	v_add_f32_e32 v107, 1.0, v107
	v_rcp_f32_e32 v106, v106
	v_rcp_f32_e32 v107, v107
	s_nop 0
	v_pk_mul_f32 v[102:103], v[102:103], v[106:107]
	v_cvt_pk_bf16_f32 v106, v100, v101
	v_mul_f32_e32 v100, 0xbfb8aa3b, v96
	v_mul_f32_e32 v101, 0xbfb8aa3b, v97
	v_exp_f32_e32 v100, v100
	v_exp_f32_e32 v101, v101
	v_cvt_pk_bf16_f32 v102, v102, v103
	v_add_f32_e32 v100, 1.0, v100
	v_add_f32_e32 v101, 1.0, v101
	v_rcp_f32_e32 v100, v100
	v_rcp_f32_e32 v101, v101
	s_nop 0
	v_pk_mul_f32 v[96:97], v[96:97], v[100:101]
	v_mul_f32_e32 v100, 0xbfb8aa3b, v98
	v_mul_f32_e32 v101, 0xbfb8aa3b, v99
	v_exp_f32_e32 v100, v100
	v_exp_f32_e32 v101, v101
	v_cvt_pk_bf16_f32 v96, v96, v97
	v_add_f32_e32 v100, 1.0, v100
	v_add_f32_e32 v101, 1.0, v101
	v_rcp_f32_e32 v100, v100
	v_rcp_f32_e32 v101, v101
	s_nop 0
	v_pk_mul_f32 v[98:99], v[98:99], v[100:101]
	s_nop 0
	v_cvt_pk_bf16_f32 v97, v98, v99
	s_waitcnt lgkmcnt(0)
	s_nop 1
	v_permlane16_swap_b32 v106, v96
	v_permlane16_swap_b32 v102, v97
	v_mov_b32_e32 v98, v106
	v_mov_b32_e32 v100, v96
	v_mov_b32_e32 v99, v102
	v_mov_b32_e32 v101, v97
	v_or_b32_e32 v96, 48, v128
	v_ashrrev_i32_e32 v97, 31, v96
	v_lshlrev_b64 v[96:97], s0, v[96:97]
	v_lshl_add_u64 v[96:97], v[96:97], 1, v[120:121]
	global_store_dwordx4 v[96:97], v[98:101], off
	s_nop 1
	v_mul_f32_e32 v98, 0xbfb8aa3b, v92
	v_mul_f32_e32 v99, 0xbfb8aa3b, v93
	v_exp_f32_e32 v98, v98
	v_exp_f32_e32 v99, v99
	v_add_f32_e32 v98, 1.0, v98
	v_add_f32_e32 v99, 1.0, v99
	v_rcp_f32_e32 v98, v98
	v_rcp_f32_e32 v99, v99
	s_nop 0
	v_pk_mul_f32 v[92:93], v[92:93], v[98:99]
	v_mul_f32_e32 v98, 0xbfb8aa3b, v94
	v_mul_f32_e32 v99, 0xbfb8aa3b, v95
	v_exp_f32_e32 v98, v98
	v_exp_f32_e32 v99, v99
	v_add_f32_e32 v98, 1.0, v98
	v_add_f32_e32 v99, 1.0, v99
	v_rcp_f32_e32 v98, v98
	v_rcp_f32_e32 v99, v99
	s_nop 0
	v_pk_mul_f32 v[94:95], v[94:95], v[98:99]
	v_cvt_pk_bf16_f32 v98, v92, v93
	v_mul_f32_e32 v92, 0xbfb8aa3b, v88
	v_mul_f32_e32 v93, 0xbfb8aa3b, v89
	v_exp_f32_e32 v92, v92
	v_exp_f32_e32 v93, v93
	v_cvt_pk_bf16_f32 v94, v94, v95
	v_add_f32_e32 v92, 1.0, v92
	v_add_f32_e32 v93, 1.0, v93
	v_rcp_f32_e32 v92, v92
	v_rcp_f32_e32 v93, v93
	s_nop 0
	v_pk_mul_f32 v[88:89], v[88:89], v[92:93]
	v_mul_f32_e32 v92, 0xbfb8aa3b, v90
	v_mul_f32_e32 v93, 0xbfb8aa3b, v91
	v_exp_f32_e32 v92, v92
	v_exp_f32_e32 v93, v93
	v_cvt_pk_bf16_f32 v88, v88, v89
	v_add_f32_e32 v92, 1.0, v92
	v_add_f32_e32 v93, 1.0, v93
	v_rcp_f32_e32 v92, v92
	v_rcp_f32_e32 v93, v93
	s_nop 0
	v_pk_mul_f32 v[90:91], v[90:91], v[92:93]
	s_nop 0
	v_cvt_pk_bf16_f32 v89, v90, v91
	s_waitcnt lgkmcnt(0)
	s_nop 1
	v_permlane16_swap_b32 v98, v88
	v_permlane16_swap_b32 v94, v89
	v_mov_b32_e32 v90, v88
	v_mov_b32_e32 v88, v98
	v_mov_b32_e32 v91, v89
	v_mov_b32_e32 v89, v94
	global_store_dwordx4 v[122:123], v[88:91], off offset:256
	s_nop 1
	v_mul_f32_e32 v88, 0xbfb8aa3b, v84
	v_mul_f32_e32 v89, 0xbfb8aa3b, v85
	v_exp_f32_e32 v88, v88
	v_exp_f32_e32 v89, v89
	v_add_f32_e32 v88, 1.0, v88
	v_add_f32_e32 v89, 1.0, v89
	v_rcp_f32_e32 v88, v88
	v_rcp_f32_e32 v89, v89
	s_nop 0
	v_pk_mul_f32 v[84:85], v[84:85], v[88:89]
	v_mul_f32_e32 v88, 0xbfb8aa3b, v86
	v_mul_f32_e32 v89, 0xbfb8aa3b, v87
	v_exp_f32_e32 v88, v88
	v_exp_f32_e32 v89, v89
	v_add_f32_e32 v88, 1.0, v88
	v_add_f32_e32 v89, 1.0, v89
	v_rcp_f32_e32 v88, v88
	v_rcp_f32_e32 v89, v89
	s_nop 0
	v_pk_mul_f32 v[86:87], v[86:87], v[88:89]
	v_cvt_pk_bf16_f32 v88, v84, v85
	v_mul_f32_e32 v84, 0xbfb8aa3b, v80
	v_mul_f32_e32 v85, 0xbfb8aa3b, v81
	v_exp_f32_e32 v84, v84
	v_exp_f32_e32 v85, v85
	v_cvt_pk_bf16_f32 v86, v86, v87
	v_add_f32_e32 v84, 1.0, v84
	v_add_f32_e32 v85, 1.0, v85
	v_rcp_f32_e32 v84, v84
	v_rcp_f32_e32 v85, v85
	s_nop 0
	v_pk_mul_f32 v[80:81], v[80:81], v[84:85]
	v_mul_f32_e32 v84, 0xbfb8aa3b, v82
	v_mul_f32_e32 v85, 0xbfb8aa3b, v83
	v_exp_f32_e32 v84, v84
	v_exp_f32_e32 v85, v85
	v_cvt_pk_bf16_f32 v80, v80, v81
	v_add_f32_e32 v84, 1.0, v84
	v_add_f32_e32 v85, 1.0, v85
	v_rcp_f32_e32 v84, v84
	v_rcp_f32_e32 v85, v85
	s_nop 0
	v_pk_mul_f32 v[82:83], v[82:83], v[84:85]
	s_nop 0
	v_cvt_pk_bf16_f32 v81, v82, v83
	s_waitcnt lgkmcnt(0)
; __device__ __forceinline__ float sigm_f(float x) { return __builtin_amdgcn_rcpf(1.f + __builtin_amdgcn_exp2f(x * -1.4426950408889634f)); }
; __device__ __forceinline__ float silu_f(float x) { return x * sigm_f(x); }
; #define SCHED __builtin_amdgcn_sched_barrier(0)
; template <int ACT>
; __device__ __forceinline__ void epi_tok(f32x4 (&acc)[2][2][4][2], bf16* __restrict__ dst, int ld, int tok0, int colbase,
;                                         const float* __restrict__ bias, float scale) {
;     ...
;   _Pragma("unroll") for (int ai = 0; ai < 2; ++ai) _Pragma("unroll") for (int bj = 0; bj < 2; ++bj) _Pragma("unroll") for (int m = 0; m < 4; ++m) {
;     uint2 pk[2];
;     _Pragma("unroll") for (int n = 0; n < 2; ++n) {
;       f32x4 v = acc[ai][bj][m][n];
;       if (ACT == 0) { _Pragma("unroll") for (int j = 0; j < 4; ++j) v[j] = silu_f(v[j]); }
;       else if (ACT == 1) { float4 b = *(const float4*)(bias + colbase + bj * 128 + t.wc * 32 + n * 16 + t.fq * 4);
;         v[0] = sigm_f(v[0] + b.x); v[1] = sigm_f(v[1] + b.y); v[2] = sigm_f(v[2] + b.z); v[3] = sigm_f(v[3] + b.w); }
;       else { _Pragma("unroll") for (int j = 0; j < 4; ++j) v[j] *= scale; }
;       pk[n] = pack4(v[0], v[1], v[2], v[3]);
;     }
;     const uint2 snd = odd ? pk[0] : pk[1];
;     uint2 rcv;
;     rcv.x = (unsigned)__builtin_amdgcn_ds_bpermute(paddr, (int)snd.x);
;     rcv.y = (unsigned)__builtin_amdgcn_ds_bpermute(paddr, (int)snd.y);
;     const u32x4 outv = odd ? u32x4{rcv.x, rcv.y, pk[1].x, pk[1].y} : u32x4{pk[0].x, pk[0].y, rcv.x, rcv.y};
;     const int row = ai * 128 + t.wr * 64 + m * 16 + t.fr;
;     const int col = bj * 128 + t.wc * 32 + (odd ? 16 + (t.fq - 1) * 4 : t.fq * 4);
;     *(u32x4*)(dst + (size_t)(tok0 + row) * ld + colbase + col) = outv;
;     SCHED;
;   }
	s_nop 1
	v_permlane16_swap_b32 v88, v80
	v_permlane16_swap_b32 v86, v81
	v_mov_b32_e32 v82, v80
	v_mov_b32_e32 v80, v88
	v_mov_b32_e32 v83, v81
	v_mov_b32_e32 v81, v86
	global_store_dwordx4 v[112:113], v[80:83], off offset:256
	s_nop 1
	v_mul_f32_e32 v80, 0xbfb8aa3b, v76
	v_mul_f32_e32 v81, 0xbfb8aa3b, v77
	v_exp_f32_e32 v80, v80
	v_exp_f32_e32 v81, v81
	v_add_f32_e32 v80, 1.0, v80
	v_add_f32_e32 v81, 1.0, v81
	v_rcp_f32_e32 v80, v80
	v_rcp_f32_e32 v81, v81
	s_nop 0
	v_pk_mul_f32 v[76:77], v[76:77], v[80:81]
	v_mul_f32_e32 v80, 0xbfb8aa3b, v78
	v_mul_f32_e32 v81, 0xbfb8aa3b, v79
	v_exp_f32_e32 v80, v80
	v_exp_f32_e32 v81, v81
	v_add_f32_e32 v80, 1.0, v80
	v_add_f32_e32 v81, 1.0, v81
	v_rcp_f32_e32 v80, v80
	v_rcp_f32_e32 v81, v81
	s_nop 0
	v_pk_mul_f32 v[78:79], v[78:79], v[80:81]
	v_cvt_pk_bf16_f32 v80, v76, v77
	v_mul_f32_e32 v76, 0xbfb8aa3b, v72
	v_mul_f32_e32 v77, 0xbfb8aa3b, v73
	v_exp_f32_e32 v76, v76
	v_exp_f32_e32 v77, v77
	v_cvt_pk_bf16_f32 v78, v78, v79
	v_add_f32_e32 v76, 1.0, v76
	v_add_f32_e32 v77, 1.0, v77
	v_rcp_f32_e32 v76, v76
	v_rcp_f32_e32 v77, v77
	s_nop 0
	v_pk_mul_f32 v[72:73], v[72:73], v[76:77]
	v_mul_f32_e32 v76, 0xbfb8aa3b, v74
	v_mul_f32_e32 v77, 0xbfb8aa3b, v75
	v_exp_f32_e32 v76, v76
	v_exp_f32_e32 v77, v77
	v_cvt_pk_bf16_f32 v72, v72, v73
	v_add_f32_e32 v76, 1.0, v76
	v_add_f32_e32 v77, 1.0, v77
	v_rcp_f32_e32 v76, v76
	v_rcp_f32_e32 v77, v77
	s_nop 0
	v_pk_mul_f32 v[74:75], v[74:75], v[76:77]
	s_nop 0
	v_cvt_pk_bf16_f32 v73, v74, v75
	s_waitcnt lgkmcnt(0)
	s_nop 1
	v_permlane16_swap_b32 v80, v72
	v_permlane16_swap_b32 v78, v73
	v_mov_b32_e32 v74, v72
	v_mov_b32_e32 v72, v80
	v_mov_b32_e32 v75, v73
	v_mov_b32_e32 v73, v78
	global_store_dwordx4 v[104:105], v[72:75], off offset:256
	s_nop 1
	v_mul_f32_e32 v72, 0xbfb8aa3b, v68
	v_mul_f32_e32 v73, 0xbfb8aa3b, v69
	v_exp_f32_e32 v72, v72
	v_exp_f32_e32 v73, v73
	v_add_f32_e32 v72, 1.0, v72
	v_add_f32_e32 v73, 1.0, v73
	v_rcp_f32_e32 v72, v72
	v_rcp_f32_e32 v73, v73
	s_nop 0
	v_pk_mul_f32 v[68:69], v[68:69], v[72:73]
	v_mul_f32_e32 v72, 0xbfb8aa3b, v70
	v_mul_f32_e32 v73, 0xbfb8aa3b, v71
	v_exp_f32_e32 v72, v72
	v_exp_f32_e32 v73, v73
	v_add_f32_e32 v72, 1.0, v72
	v_add_f32_e32 v73, 1.0, v73
	v_rcp_f32_e32 v72, v72
	v_rcp_f32_e32 v73, v73
	s_nop 0
	v_pk_mul_f32 v[70:71], v[70:71], v[72:73]
	v_cvt_pk_bf16_f32 v72, v68, v69
	v_mul_f32_e32 v68, 0xbfb8aa3b, v64
	v_mul_f32_e32 v69, 0xbfb8aa3b, v65
	v_exp_f32_e32 v68, v68
	v_exp_f32_e32 v69, v69
	v_cvt_pk_bf16_f32 v70, v70, v71
	v_add_f32_e32 v68, 1.0, v68
	v_add_f32_e32 v69, 1.0, v69
	v_rcp_f32_e32 v68, v68
	v_rcp_f32_e32 v69, v69
	s_nop 0
	v_pk_mul_f32 v[64:65], v[64:65], v[68:69]
	v_mul_f32_e32 v68, 0xbfb8aa3b, v66
	v_mul_f32_e32 v69, 0xbfb8aa3b, v67
	v_exp_f32_e32 v68, v68
	v_exp_f32_e32 v69, v69
	v_cvt_pk_bf16_f32 v64, v64, v65
	v_add_f32_e32 v68, 1.0, v68
	v_add_f32_e32 v69, 1.0, v69
	v_rcp_f32_e32 v68, v68
	v_rcp_f32_e32 v69, v69
	s_nop 0
	v_pk_mul_f32 v[66:67], v[66:67], v[68:69]
	s_nop 0
	v_cvt_pk_bf16_f32 v65, v66, v67
	s_waitcnt lgkmcnt(0)
	s_nop 1
	v_permlane16_swap_b32 v72, v64
	v_permlane16_swap_b32 v70, v65
	v_mov_b32_e32 v66, v64
	v_mov_b32_e32 v64, v72
	v_mov_b32_e32 v67, v65
	v_mov_b32_e32 v65, v70
	global_store_dwordx4 v[96:97], v[64:67], off offset:256
	s_nop 1
	v_mul_f32_e32 v64, 0xbfb8aa3b, v60
	v_mul_f32_e32 v65, 0xbfb8aa3b, v61
	v_exp_f32_e32 v64, v64
	v_exp_f32_e32 v65, v65
	v_mul_f32_e32 v66, 0xbfb8aa3b, v62
	v_mul_f32_e32 v67, 0xbfb8aa3b, v63
	v_add_f32_e32 v64, 1.0, v64
	v_add_f32_e32 v65, 1.0, v65
	v_rcp_f32_e32 v64, v64
	v_rcp_f32_e32 v65, v65
	v_exp_f32_e32 v66, v66
	v_exp_f32_e32 v67, v67
	v_pk_mul_f32 v[60:61], v[60:61], v[64:65]
	v_add_f32_e32 v64, 1.0, v66
	v_add_f32_e32 v65, 1.0, v67
	v_mul_f32_e32 v66, 0xbfb8aa3b, v56
	v_mul_f32_e32 v67, 0xbfb8aa3b, v57
	v_rcp_f32_e32 v64, v64
	v_rcp_f32_e32 v65, v65
	v_exp_f32_e32 v66, v66
	v_exp_f32_e32 v67, v67
	v_cvt_pk_bf16_f32 v68, v60, v61
	v_pk_mul_f32 v[62:63], v[62:63], v[64:65]
	v_add_f32_e32 v64, 1.0, v66
	v_add_f32_e32 v65, 1.0, v67
	v_mul_f32_e32 v66, 0xbfb8aa3b, v58
	v_mul_f32_e32 v67, 0xbfb8aa3b, v59
	v_exp_f32_e32 v66, v66
	v_exp_f32_e32 v67, v67
	v_rcp_f32_e32 v64, v64
	v_rcp_f32_e32 v65, v65
	v_add_f32_e32 v66, 1.0, v66
	v_add_f32_e32 v67, 1.0, v67
	v_rcp_f32_e32 v66, v66
	v_rcp_f32_e32 v67, v67
	v_pk_mul_f32 v[56:57], v[56:57], v[64:65]
	v_cvt_pk_bf16_f32 v62, v62, v63
	v_cvt_pk_bf16_f32 v57, v56, v57
	v_pk_mul_f32 v[58:59], v[58:59], v[66:67]
	v_cvt_pk_bf16_f32 v58, v58, v59
	v_add_u32_e32 v56, 0x80, v128
	s_waitcnt lgkmcnt(0)
	s_nop 1
	v_permlane16_swap_b32 v68, v57
	v_permlane16_swap_b32 v62, v58
	v_mov_b32_e32 v60, v57
	v_mov_b32_e32 v59, v62
	v_mov_b32_e32 v61, v58
	v_mov_b32_e32 v58, v68
	v_ashrrev_i32_e32 v57, 31, v56
	v_lshlrev_b64 v[56:57], s0, v[56:57]
	v_lshl_add_u64 v[56:57], v[56:57], 1, v[120:121]
	global_store_dwordx4 v[56:57], v[58:61], off
	s_nop 1
	v_mul_f32_e32 v58, 0xbfb8aa3b, v52
	v_mul_f32_e32 v59, 0xbfb8aa3b, v53
	v_exp_f32_e32 v58, v58
	v_exp_f32_e32 v59, v59
	v_add_f32_e32 v58, 1.0, v58
	v_add_f32_e32 v59, 1.0, v59
	v_rcp_f32_e32 v58, v58
	v_rcp_f32_e32 v59, v59
	s_nop 0
	v_pk_mul_f32 v[52:53], v[52:53], v[58:59]
	v_mul_f32_e32 v58, 0xbfb8aa3b, v54
	v_mul_f32_e32 v59, 0xbfb8aa3b, v55
	v_exp_f32_e32 v58, v58
	v_exp_f32_e32 v59, v59
	v_add_f32_e32 v58, 1.0, v58
	v_add_f32_e32 v59, 1.0, v59
	v_rcp_f32_e32 v58, v58
	v_rcp_f32_e32 v59, v59
	s_nop 0
	v_pk_mul_f32 v[54:55], v[54:55], v[58:59]
	v_cvt_pk_bf16_f32 v58, v52, v53
	v_mul_f32_e32 v52, 0xbfb8aa3b, v48
	v_mul_f32_e32 v53, 0xbfb8aa3b, v49
	v_exp_f32_e32 v52, v52
	v_exp_f32_e32 v53, v53
	v_cvt_pk_bf16_f32 v54, v54, v55
	v_add_f32_e32 v52, 1.0, v52
	v_add_f32_e32 v53, 1.0, v53
	v_rcp_f32_e32 v52, v52
	v_rcp_f32_e32 v53, v53
	s_nop 0
	v_pk_mul_f32 v[48:49], v[48:49], v[52:53]
	v_mul_f32_e32 v52, 0xbfb8aa3b, v50
	v_mul_f32_e32 v53, 0xbfb8aa3b, v51
	v_exp_f32_e32 v52, v52
	v_exp_f32_e32 v53, v53
	v_cvt_pk_bf16_f32 v48, v48, v49
	v_add_f32_e32 v52, 1.0, v52
	v_add_f32_e32 v53, 1.0, v53
	v_rcp_f32_e32 v52, v52
	v_rcp_f32_e32 v53, v53
	s_nop 0
	v_pk_mul_f32 v[50:51], v[50:51], v[52:53]
	s_nop 0
	v_cvt_pk_bf16_f32 v49, v50, v51
	s_waitcnt lgkmcnt(0)
; __device__ __forceinline__ float sigm_f(float x) { return __builtin_amdgcn_rcpf(1.f + __builtin_amdgcn_exp2f(x * -1.4426950408889634f)); }
; __device__ __forceinline__ float silu_f(float x) { return x * sigm_f(x); }
; #define SCHED __builtin_amdgcn_sched_barrier(0)
; template <int ACT>
; __device__ __forceinline__ void epi_tok(f32x4 (&acc)[2][2][4][2], bf16* __restrict__ dst, int ld, int tok0, int colbase,
;                                         const float* __restrict__ bias, float scale) {
;     ...
;   _Pragma("unroll") for (int ai = 0; ai < 2; ++ai) _Pragma("unroll") for (int bj = 0; bj < 2; ++bj) _Pragma("unroll") for (int m = 0; m < 4; ++m) {
;     uint2 pk[2];
;     _Pragma("unroll") for (int n = 0; n < 2; ++n) {
;       f32x4 v = acc[ai][bj][m][n];
;       if (ACT == 0) { _Pragma("unroll") for (int j = 0; j < 4; ++j) v[j] = silu_f(v[j]); }
;       else if (ACT == 1) { float4 b = *(const float4*)(bias + colbase + bj * 128 + t.wc * 32 + n * 16 + t.fq * 4);
;         v[0] = sigm_f(v[0] + b.x); v[1] = sigm_f(v[1] + b.y); v[2] = sigm_f(v[2] + b.z); v[3] = sigm_f(v[3] + b.w); }
;       else { _Pragma("unroll") for (int j = 0; j < 4; ++j) v[j] *= scale; }
;       pk[n] = pack4(v[0], v[1], v[2], v[3]);
;     }
;     const uint2 snd = odd ? pk[0] : pk[1];
;     uint2 rcv;
;     rcv.x = (unsigned)__builtin_amdgcn_ds_bpermute(paddr, (int)snd.x);
;     rcv.y = (unsigned)__builtin_amdgcn_ds_bpermute(paddr, (int)snd.y);
;     const u32x4 outv = odd ? u32x4{rcv.x, rcv.y, pk[1].x, pk[1].y} : u32x4{pk[0].x, pk[0].y, rcv.x, rcv.y};
;     const int row = ai * 128 + t.wr * 64 + m * 16 + t.fr;
;     const int col = bj * 128 + t.wc * 32 + (odd ? 16 + (t.fq - 1) * 4 : t.fq * 4);
;     *(u32x4*)(dst + (size_t)(tok0 + row) * ld + colbase + col) = outv;
;     SCHED;
;   }
	s_nop 1
	v_permlane16_swap_b32 v58, v48
	v_permlane16_swap_b32 v54, v49
	v_mov_b32_e32 v50, v58
	v_mov_b32_e32 v52, v48
	v_mov_b32_e32 v51, v54
	v_mov_b32_e32 v53, v49
	v_add_u32_e32 v48, 0x90, v128
	v_ashrrev_i32_e32 v49, 31, v48
	v_lshlrev_b64 v[48:49], s0, v[48:49]
	v_lshl_add_u64 v[48:49], v[48:49], 1, v[120:121]
	global_store_dwordx4 v[48:49], v[50:53], off
	s_nop 1
	v_mul_f32_e32 v50, 0xbfb8aa3b, v44
	v_mul_f32_e32 v51, 0xbfb8aa3b, v45
	v_exp_f32_e32 v50, v50
	v_exp_f32_e32 v51, v51
	v_add_f32_e32 v50, 1.0, v50
	v_add_f32_e32 v51, 1.0, v51
	v_rcp_f32_e32 v50, v50
	v_rcp_f32_e32 v51, v51
	s_nop 0
	v_pk_mul_f32 v[44:45], v[44:45], v[50:51]
	v_mul_f32_e32 v50, 0xbfb8aa3b, v46
	v_mul_f32_e32 v51, 0xbfb8aa3b, v47
	v_exp_f32_e32 v50, v50
	v_exp_f32_e32 v51, v51
	v_add_f32_e32 v50, 1.0, v50
	v_add_f32_e32 v51, 1.0, v51
	v_rcp_f32_e32 v50, v50
	v_rcp_f32_e32 v51, v51
	s_nop 0
	v_pk_mul_f32 v[46:47], v[46:47], v[50:51]
	v_cvt_pk_bf16_f32 v50, v44, v45
	v_mul_f32_e32 v44, 0xbfb8aa3b, v40
	v_mul_f32_e32 v45, 0xbfb8aa3b, v41
	v_exp_f32_e32 v44, v44
	v_exp_f32_e32 v45, v45
	v_cvt_pk_bf16_f32 v46, v46, v47
	v_add_f32_e32 v44, 1.0, v44
	v_add_f32_e32 v45, 1.0, v45
	v_rcp_f32_e32 v44, v44
	v_rcp_f32_e32 v45, v45
	s_nop 0
	v_pk_mul_f32 v[40:41], v[40:41], v[44:45]
	v_mul_f32_e32 v44, 0xbfb8aa3b, v42
	v_mul_f32_e32 v45, 0xbfb8aa3b, v43
	v_exp_f32_e32 v44, v44
	v_exp_f32_e32 v45, v45
	v_cvt_pk_bf16_f32 v40, v40, v41
	v_add_f32_e32 v44, 1.0, v44
	v_add_f32_e32 v45, 1.0, v45
	v_rcp_f32_e32 v44, v44
	v_rcp_f32_e32 v45, v45
	s_nop 0
	v_pk_mul_f32 v[42:43], v[42:43], v[44:45]
	s_nop 0
	v_cvt_pk_bf16_f32 v41, v42, v43
	s_waitcnt lgkmcnt(0)
	s_nop 1
	v_permlane16_swap_b32 v50, v40
	v_permlane16_swap_b32 v46, v41
	v_mov_b32_e32 v42, v50
	v_mov_b32_e32 v44, v40
	v_mov_b32_e32 v43, v46
	v_mov_b32_e32 v45, v41
	v_add_u32_e32 v40, 0xa0, v128
	v_ashrrev_i32_e32 v41, 31, v40
	v_lshlrev_b64 v[40:41], s0, v[40:41]
	v_lshl_add_u64 v[40:41], v[40:41], 1, v[120:121]
	global_store_dwordx4 v[40:41], v[42:45], off
	s_nop 1
	v_mul_f32_e32 v42, 0xbfb8aa3b, v36
	v_mul_f32_e32 v43, 0xbfb8aa3b, v37
	v_exp_f32_e32 v42, v42
	v_exp_f32_e32 v43, v43
	v_add_f32_e32 v42, 1.0, v42
	v_add_f32_e32 v43, 1.0, v43
	v_rcp_f32_e32 v42, v42
	v_rcp_f32_e32 v43, v43
	s_nop 0
	v_pk_mul_f32 v[36:37], v[36:37], v[42:43]
	v_mul_f32_e32 v42, 0xbfb8aa3b, v38
	v_mul_f32_e32 v43, 0xbfb8aa3b, v39
	v_exp_f32_e32 v42, v42
	v_exp_f32_e32 v43, v43
	v_add_f32_e32 v42, 1.0, v42
	v_add_f32_e32 v43, 1.0, v43
	v_rcp_f32_e32 v42, v42
	v_rcp_f32_e32 v43, v43
	s_nop 0
	v_pk_mul_f32 v[38:39], v[38:39], v[42:43]
	v_cvt_pk_bf16_f32 v42, v36, v37
	v_mul_f32_e32 v36, 0xbfb8aa3b, v32
	v_mul_f32_e32 v37, 0xbfb8aa3b, v33
	v_exp_f32_e32 v36, v36
	v_exp_f32_e32 v37, v37
	v_cvt_pk_bf16_f32 v38, v38, v39
	v_add_f32_e32 v36, 1.0, v36
	v_add_f32_e32 v37, 1.0, v37
	v_rcp_f32_e32 v36, v36
	v_rcp_f32_e32 v37, v37
	s_nop 0
	v_pk_mul_f32 v[32:33], v[32:33], v[36:37]
	v_mul_f32_e32 v36, 0xbfb8aa3b, v34
	v_mul_f32_e32 v37, 0xbfb8aa3b, v35
	v_exp_f32_e32 v36, v36
	v_exp_f32_e32 v37, v37
	v_cvt_pk_bf16_f32 v32, v32, v33
	v_add_f32_e32 v36, 1.0, v36
	v_add_f32_e32 v37, 1.0, v37
	v_rcp_f32_e32 v36, v36
	v_rcp_f32_e32 v37, v37
	s_nop 0
	v_pk_mul_f32 v[34:35], v[34:35], v[36:37]
	s_nop 0
	v_cvt_pk_bf16_f32 v33, v34, v35
	s_waitcnt lgkmcnt(0)
	s_nop 1
	v_permlane16_swap_b32 v42, v32
	v_permlane16_swap_b32 v38, v33
	v_mov_b32_e32 v34, v42
	v_mov_b32_e32 v36, v32
	v_mov_b32_e32 v35, v38
	v_mov_b32_e32 v37, v33
	v_add_u32_e32 v32, 0xb0, v128
	v_ashrrev_i32_e32 v33, 31, v32
	v_lshlrev_b64 v[32:33], s0, v[32:33]
	v_lshl_add_u64 v[32:33], v[32:33], 1, v[120:121]
	global_store_dwordx4 v[32:33], v[34:37], off
	s_nop 1
	v_mul_f32_e32 v34, 0xbfb8aa3b, v28
	v_mul_f32_e32 v35, 0xbfb8aa3b, v29
	v_exp_f32_e32 v34, v34
	v_exp_f32_e32 v35, v35
	v_add_f32_e32 v34, 1.0, v34
	v_add_f32_e32 v35, 1.0, v35
	v_rcp_f32_e32 v34, v34
	v_rcp_f32_e32 v35, v35
	s_nop 0
	v_pk_mul_f32 v[28:29], v[28:29], v[34:35]
	v_mul_f32_e32 v34, 0xbfb8aa3b, v30
	v_mul_f32_e32 v35, 0xbfb8aa3b, v31
	v_exp_f32_e32 v34, v34
	v_exp_f32_e32 v35, v35
	v_add_f32_e32 v34, 1.0, v34
	v_add_f32_e32 v35, 1.0, v35
	v_rcp_f32_e32 v34, v34
	v_rcp_f32_e32 v35, v35
	s_nop 0
	v_pk_mul_f32 v[30:31], v[30:31], v[34:35]
	v_cvt_pk_bf16_f32 v34, v28, v29
	v_mul_f32_e32 v28, 0xbfb8aa3b, v24
	v_mul_f32_e32 v29, 0xbfb8aa3b, v25
	v_exp_f32_e32 v28, v28
	v_exp_f32_e32 v29, v29
	v_cvt_pk_bf16_f32 v30, v30, v31
	v_add_f32_e32 v28, 1.0, v28
	v_add_f32_e32 v29, 1.0, v29
	v_rcp_f32_e32 v28, v28
	v_rcp_f32_e32 v29, v29
	s_nop 0
	v_pk_mul_f32 v[24:25], v[24:25], v[28:29]
	v_mul_f32_e32 v28, 0xbfb8aa3b, v26
	v_mul_f32_e32 v29, 0xbfb8aa3b, v27
	v_exp_f32_e32 v28, v28
	v_exp_f32_e32 v29, v29
	v_cvt_pk_bf16_f32 v24, v24, v25
	v_add_f32_e32 v28, 1.0, v28
	v_add_f32_e32 v29, 1.0, v29
	v_rcp_f32_e32 v28, v28
	v_rcp_f32_e32 v29, v29
	s_nop 0
	v_pk_mul_f32 v[26:27], v[26:27], v[28:29]
	s_nop 0
	v_cvt_pk_bf16_f32 v25, v26, v27
	s_waitcnt lgkmcnt(0)
; __device__ __forceinline__ float sigm_f(float x) { return __builtin_amdgcn_rcpf(1.f + __builtin_amdgcn_exp2f(x * -1.4426950408889634f)); }
; __device__ __forceinline__ float silu_f(float x) { return x * sigm_f(x); }
; #define SCHED __builtin_amdgcn_sched_barrier(0)
; template <int ACT>
; __device__ __forceinline__ void epi_tok(f32x4 (&acc)[2][2][4][2], bf16* __restrict__ dst, int ld, int tok0, int colbase,
;                                         const float* __restrict__ bias, float scale) {
;     ...
;   _Pragma("unroll") for (int ai = 0; ai < 2; ++ai) _Pragma("unroll") for (int bj = 0; bj < 2; ++bj) _Pragma("unroll") for (int m = 0; m < 4; ++m) {
;     uint2 pk[2];
;     _Pragma("unroll") for (int n = 0; n < 2; ++n) {
;       f32x4 v = acc[ai][bj][m][n];
;       if (ACT == 0) { _Pragma("unroll") for (int j = 0; j < 4; ++j) v[j] = silu_f(v[j]); }
;       else if (ACT == 1) { float4 b = *(const float4*)(bias + colbase + bj * 128 + t.wc * 32 + n * 16 + t.fq * 4);
;         v[0] = sigm_f(v[0] + b.x); v[1] = sigm_f(v[1] + b.y); v[2] = sigm_f(v[2] + b.z); v[3] = sigm_f(v[3] + b.w); }
;       else { _Pragma("unroll") for (int j = 0; j < 4; ++j) v[j] *= scale; }
;       pk[n] = pack4(v[0], v[1], v[2], v[3]);
;     }
;     const uint2 snd = odd ? pk[0] : pk[1];
;     uint2 rcv;
;     rcv.x = (unsigned)__builtin_amdgcn_ds_bpermute(paddr, (int)snd.x);
;     rcv.y = (unsigned)__builtin_amdgcn_ds_bpermute(paddr, (int)snd.y);
;     const u32x4 outv = odd ? u32x4{rcv.x, rcv.y, pk[1].x, pk[1].y} : u32x4{pk[0].x, pk[0].y, rcv.x, rcv.y};
;     const int row = ai * 128 + t.wr * 64 + m * 16 + t.fr;
;     const int col = bj * 128 + t.wc * 32 + (odd ? 16 + (t.fq - 1) * 4 : t.fq * 4);
;     *(u32x4*)(dst + (size_t)(tok0 + row) * ld + colbase + col) = outv;
;     SCHED;
;   }
	s_nop 1
	v_permlane16_swap_b32 v34, v24
	v_permlane16_swap_b32 v30, v25
	v_mov_b32_e32 v26, v24
	v_mov_b32_e32 v24, v34
	v_mov_b32_e32 v27, v25
	v_mov_b32_e32 v25, v30
	global_store_dwordx4 v[56:57], v[24:27], off offset:256
	s_nop 1
	v_mul_f32_e32 v24, 0xbfb8aa3b, v20
	v_mul_f32_e32 v25, 0xbfb8aa3b, v21
	v_exp_f32_e32 v24, v24
	v_exp_f32_e32 v25, v25
	v_add_f32_e32 v24, 1.0, v24
	v_add_f32_e32 v25, 1.0, v25
	v_rcp_f32_e32 v24, v24
	v_rcp_f32_e32 v25, v25
	s_nop 0
	v_pk_mul_f32 v[20:21], v[20:21], v[24:25]
	v_mul_f32_e32 v24, 0xbfb8aa3b, v22
	v_mul_f32_e32 v25, 0xbfb8aa3b, v23
	v_exp_f32_e32 v24, v24
	v_exp_f32_e32 v25, v25
	v_add_f32_e32 v24, 1.0, v24
	v_add_f32_e32 v25, 1.0, v25
	v_rcp_f32_e32 v24, v24
	v_rcp_f32_e32 v25, v25
	s_nop 0
	v_pk_mul_f32 v[22:23], v[22:23], v[24:25]
	v_cvt_pk_bf16_f32 v24, v20, v21
	v_mul_f32_e32 v20, 0xbfb8aa3b, v16
	v_mul_f32_e32 v21, 0xbfb8aa3b, v17
	v_exp_f32_e32 v20, v20
	v_exp_f32_e32 v21, v21
	v_cvt_pk_bf16_f32 v22, v22, v23
	v_add_f32_e32 v20, 1.0, v20
	v_add_f32_e32 v21, 1.0, v21
	v_rcp_f32_e32 v20, v20
	v_rcp_f32_e32 v21, v21
	s_nop 0
	v_pk_mul_f32 v[16:17], v[16:17], v[20:21]
	v_mul_f32_e32 v20, 0xbfb8aa3b, v18
	v_mul_f32_e32 v21, 0xbfb8aa3b, v19
	v_exp_f32_e32 v20, v20
	v_exp_f32_e32 v21, v21
	v_cvt_pk_bf16_f32 v16, v16, v17
	v_add_f32_e32 v20, 1.0, v20
	v_add_f32_e32 v21, 1.0, v21
	v_rcp_f32_e32 v20, v20
	v_rcp_f32_e32 v21, v21
	s_nop 0
	v_pk_mul_f32 v[18:19], v[18:19], v[20:21]
	s_nop 0
	v_cvt_pk_bf16_f32 v17, v18, v19
	s_waitcnt lgkmcnt(0)
	s_nop 1
	v_permlane16_swap_b32 v24, v16
	v_permlane16_swap_b32 v22, v17
	v_mov_b32_e32 v18, v16
	v_mov_b32_e32 v16, v24
	v_mov_b32_e32 v19, v17
	v_mov_b32_e32 v17, v22
	global_store_dwordx4 v[48:49], v[16:19], off offset:256
	s_nop 1
	v_mul_f32_e32 v16, 0xbfb8aa3b, v12
	v_mul_f32_e32 v17, 0xbfb8aa3b, v13
	v_exp_f32_e32 v16, v16
	v_exp_f32_e32 v17, v17
	v_add_f32_e32 v16, 1.0, v16
	v_add_f32_e32 v17, 1.0, v17
	v_rcp_f32_e32 v16, v16
	v_rcp_f32_e32 v17, v17
	s_nop 0
	v_pk_mul_f32 v[12:13], v[12:13], v[16:17]
	v_mul_f32_e32 v16, 0xbfb8aa3b, v14
	v_mul_f32_e32 v17, 0xbfb8aa3b, v15
	v_exp_f32_e32 v16, v16
	v_exp_f32_e32 v17, v17
	v_add_f32_e32 v16, 1.0, v16
	v_add_f32_e32 v17, 1.0, v17
	v_rcp_f32_e32 v16, v16
	v_rcp_f32_e32 v17, v17
	s_nop 0
	v_pk_mul_f32 v[14:15], v[14:15], v[16:17]
	v_cvt_pk_bf16_f32 v16, v12, v13
	v_mul_f32_e32 v12, 0xbfb8aa3b, v8
	v_mul_f32_e32 v13, 0xbfb8aa3b, v9
	v_exp_f32_e32 v12, v12
	v_exp_f32_e32 v13, v13
	v_cvt_pk_bf16_f32 v14, v14, v15
	v_add_f32_e32 v12, 1.0, v12
	v_add_f32_e32 v13, 1.0, v13
	v_rcp_f32_e32 v12, v12
	v_rcp_f32_e32 v13, v13
	s_nop 0
	v_pk_mul_f32 v[8:9], v[8:9], v[12:13]
	v_mul_f32_e32 v12, 0xbfb8aa3b, v10
	v_mul_f32_e32 v13, 0xbfb8aa3b, v11
	v_exp_f32_e32 v12, v12
	v_exp_f32_e32 v13, v13
	v_cvt_pk_bf16_f32 v8, v8, v9
	v_add_f32_e32 v12, 1.0, v12
	v_add_f32_e32 v13, 1.0, v13
	v_rcp_f32_e32 v12, v12
	v_rcp_f32_e32 v13, v13
	s_nop 0
	v_pk_mul_f32 v[10:11], v[10:11], v[12:13]
	s_nop 0
	v_cvt_pk_bf16_f32 v9, v10, v11
	s_waitcnt lgkmcnt(0)
	s_nop 1
	v_permlane16_swap_b32 v16, v8
	v_permlane16_swap_b32 v14, v9
	v_mov_b32_e32 v10, v8
	v_mov_b32_e32 v8, v16
	v_mov_b32_e32 v11, v9
	v_mov_b32_e32 v9, v14
	global_store_dwordx4 v[40:41], v[8:11], off offset:256
	s_nop 1
	v_mul_f32_e32 v8, 0xbfb8aa3b, v4
	v_mul_f32_e32 v9, 0xbfb8aa3b, v5
	v_exp_f32_e32 v8, v8
	v_exp_f32_e32 v9, v9
	v_add_f32_e32 v8, 1.0, v8
	v_add_f32_e32 v9, 1.0, v9
	v_rcp_f32_e32 v8, v8
	v_rcp_f32_e32 v9, v9
	s_nop 0
	v_pk_mul_f32 v[4:5], v[4:5], v[8:9]
	v_mul_f32_e32 v8, 0xbfb8aa3b, v6
	v_mul_f32_e32 v9, 0xbfb8aa3b, v7
	v_exp_f32_e32 v8, v8
	v_exp_f32_e32 v9, v9
	v_add_f32_e32 v8, 1.0, v8
	v_add_f32_e32 v9, 1.0, v9
	v_rcp_f32_e32 v8, v8
	v_rcp_f32_e32 v9, v9
	s_nop 0
	v_pk_mul_f32 v[6:7], v[6:7], v[8:9]
	v_cvt_pk_bf16_f32 v8, v4, v5
	v_mul_f32_e32 v4, 0xbfb8aa3b, v0
	v_mul_f32_e32 v5, 0xbfb8aa3b, v1
	v_exp_f32_e32 v4, v4
	v_exp_f32_e32 v5, v5
	v_cvt_pk_bf16_f32 v6, v6, v7
	v_add_f32_e32 v4, 1.0, v4
	v_add_f32_e32 v5, 1.0, v5
	v_rcp_f32_e32 v4, v4
	v_rcp_f32_e32 v5, v5
	s_nop 0
	v_pk_mul_f32 v[0:1], v[0:1], v[4:5]
	v_mul_f32_e32 v4, 0xbfb8aa3b, v2
	v_mul_f32_e32 v5, 0xbfb8aa3b, v3
	v_exp_f32_e32 v4, v4
	v_exp_f32_e32 v5, v5
	v_cvt_pk_bf16_f32 v0, v0, v1
	v_add_f32_e32 v4, 1.0, v4
	v_add_f32_e32 v5, 1.0, v5
	v_rcp_f32_e32 v4, v4
	v_rcp_f32_e32 v5, v5
	s_nop 0
	v_pk_mul_f32 v[2:3], v[2:3], v[4:5]
	s_nop 0
	v_cvt_pk_bf16_f32 v1, v2, v3
	s_waitcnt lgkmcnt(0)
	s_nop 1
	v_permlane16_swap_b32 v8, v0
	v_permlane16_swap_b32 v6, v1
	v_mov_b32_e32 v2, v0
	v_mov_b32_e32 v0, v8
	v_mov_b32_e32 v3, v1
	v_mov_b32_e32 v1, v6
	global_store_dwordx4 v[32:33], v[0:3], off offset:256
	s_mov_b64 s[14:15], -1
	s_and_b64 vcc, exec, s[4:5]
	s_cbranch_vccnz .LBB0_519

; __device__ __forceinline__ float sigm_f(float x) { return __builtin_amdgcn_rcpf(1.f + __builtin_amdgcn_exp2f(x * -1.4426950408889634f)); }
; __device__ __forceinline__ float silu_f(float x) { return x * sigm_f(x); }
; #define SCHED __builtin_amdgcn_sched_barrier(0)
; template <int ACT>
; __device__ __forceinline__ void epi_tok(f32x4 (&acc)[2][2][4][2], bf16* __restrict__ dst, int ld, int tok0, int colbase,
;                                         const float* __restrict__ bias, float scale) {
;   TC t = get_tc();
;   const int odd = t.fq & 1;
;   const int paddr = ((t.fq ^ 1) * 16 + t.fr) << 2;
;   _Pragma("unroll") for (int ai = 0; ai < 2; ++ai) _Pragma("unroll") for (int bj = 0; bj < 2; ++bj) _Pragma("unroll") for (int m = 0; m < 4; ++m) {
;     uint2 pk[2];
;     _Pragma("unroll") for (int n = 0; n < 2; ++n) {
;       f32x4 v = acc[ai][bj][m][n];
;       if (ACT == 0) { _Pragma("unroll") for (int j = 0; j < 4; ++j) v[j] = silu_f(v[j]); }
;       else if (ACT == 1) { float4 b = *(const float4*)(bias + colbase + bj * 128 + t.wc * 32 + n * 16 + t.fq * 4);
;         v[0] = sigm_f(v[0] + b.x); v[1] = sigm_f(v[1] + b.y); v[2] = sigm_f(v[2] + b.z); v[3] = sigm_f(v[3] + b.w); }
;       else { _Pragma("unroll") for (int j = 0; j < 4; ++j) v[j] *= scale; }
;       pk[n] = pack4(v[0], v[1], v[2], v[3]);
;     }
;     const uint2 snd = odd ? pk[0] : pk[1];
;     uint2 rcv;
;     rcv.x = (unsigned)__builtin_amdgcn_ds_bpermute(paddr, (int)snd.x);
;     rcv.y = (unsigned)__builtin_amdgcn_ds_bpermute(paddr, (int)snd.y);
;     const u32x4 outv = odd ? u32x4{rcv.x, rcv.y, pk[1].x, pk[1].y} : u32x4{pk[0].x, pk[0].y, rcv.x, rcv.y};
;     const int row = ai * 128 + t.wr * 64 + m * 16 + t.fr;
;     const int col = bj * 128 + t.wc * 32 + (odd ? 16 + (t.fq - 1) * 4 : t.fq * 4);
;     *(u32x4*)(dst + (size_t)(tok0 + row) * ld + colbase + col) = outv;
;     SCHED;
;   }
; }
; __device__ __forceinline__ void phase_inproj(const Params& p, const Grp& g, int l) {
;     ...
;       bf16* dst = (ci < 4) ? Q : KB;
;       const int ld = (ci < 4) ? 1024 : 256, colbase = (ci < 4) ? ci * 256 : 0;
;       epi_tok<2>(acc, dst, ld, tok0, colbase, nullptr, (ci < 4) ? QSCALE : 1.f);
.LBB0_521:
	s_or_b64 exec, exec, s[8:9]
	s_cmp_lt_i32 s40, 4
	s_cselect_b64 s[8:9], -1, 0
	s_and_b64 s[8:9], s[8:9], exec
	s_cselect_b32 s7, 10, 8
	s_lshl_b32 s10, s40, 8
	s_cmp_lt_i32 s40, 4
	v_mov_b32_e32 v130, v190
	s_cselect_b64 vcc, -1, 0
	v_cndmask_b32_e32 v128, 1.0, v196, vcc
	v_lshlrev_b32_e32 v129, 2, v130
	v_bitop3_b32 v129, v129, 64, v194 bitop3:0x6c
	s_and_b64 s[8:9], vcc, exec
	v_and_b32_e32 v131, 16, v130
	v_lshrrev_b32_e32 v134, 2, v130
	v_pk_mul_f32 v[124:125], v[128:129], v[124:125] op_sel_hi:[0,1]
	v_pk_mul_f32 v[126:127], v[128:129], v[126:127] op_sel_hi:[0,1]
	v_pk_mul_f32 v[86:87], v[128:129], v[86:87] op_sel_hi:[0,1]
	s_mov_b32 s8, 0x17260000
	v_and_b32_e32 v134, 12, v134
	v_cmp_eq_u32_e32 vcc, 0, v131
	v_cvt_pk_bf16_f32 v124, v124, v125
	v_cvt_pk_bf16_f32 v125, v126, v127
	v_pk_mul_f32 v[84:85], v[128:129], v[84:85] op_sel_hi:[0,1]
	v_cvt_pk_bf16_f32 v86, v86, v87
	s_cselect_b32 s9, s8, 0x1f260000
	v_ashrrev_i32_e32 v132, 2, v130
	v_add_u32_e32 v135, 12, v134
	v_cvt_pk_bf16_f32 v126, v84, v85
	s_cselect_b32 s8, s10, 0
	s_add_u32 s10, s58, s9
	v_and_b32_e32 v132, 0xffffffc0, v132
	v_lshrrev_b32_e32 v133, 1, v130
	v_cndmask_b32_e32 v131, v135, v134, vcc
	s_movk_i32 s9, 0x60
	v_and_or_b32 v130, v130, 15, s6
	s_addc_u32 s11, s59, 0
	v_and_or_b32 v131, v133, s9, v131
	v_add_u32_e32 v130, v130, v132
	s_ashr_i32 s9, s8, 31
	s_lshl_b64 s[8:9], s[8:9], 1
	s_add_u32 s8, s10, s8
	s_addc_u32 s9, s11, s9
	v_lshlrev_b32_e32 v186, 1, v131
	v_ashrrev_i32_e32 v131, 31, v130
	v_lshl_add_u64 v[84:85], s[8:9], 0, v[186:187]
	s_waitcnt lgkmcnt(0)
	s_nop 1
	v_permlane16_swap_b32 v125, v86
	v_permlane16_swap_b32 v124, v126
	v_mov_b32_e32 v127, v86
	v_lshlrev_b64 v[86:87], s7, v[130:131]
	v_lshl_add_u64 v[86:87], v[86:87], 1, v[84:85]
	global_store_dwordx4 v[86:87], v[124:127], off
	v_pk_mul_f32 v[120:121], v[128:129], v[120:121] op_sel_hi:[0,1]
	v_pk_mul_f32 v[72:73], v[128:129], v[72:73] op_sel_hi:[0,1]
	v_pk_mul_f32 v[122:123], v[128:129], v[122:123] op_sel_hi:[0,1]
	v_cvt_pk_bf16_f32 v120, v120, v121
	v_pk_mul_f32 v[74:75], v[128:129], v[74:75] op_sel_hi:[0,1]
	v_cvt_pk_bf16_f32 v72, v72, v73
	v_cvt_pk_bf16_f32 v121, v122, v123
	v_cvt_pk_bf16_f32 v73, v74, v75
	s_waitcnt lgkmcnt(0)
	s_nop 1
	v_permlane16_swap_b32 v120, v72
	v_permlane16_swap_b32 v121, v73
	v_mov_b32_e32 v74, v72
	v_mov_b32_e32 v72, v120
	v_mov_b32_e32 v75, v73
	v_mov_b32_e32 v73, v121
	v_or_b32_e32 v120, 16, v130
	v_ashrrev_i32_e32 v121, 31, v120
	v_lshlrev_b64 v[120:121], s7, v[120:121]
	v_lshl_add_u64 v[120:121], v[120:121], 1, v[84:85]
	global_store_dwordx4 v[120:121], v[72:75], off
	s_nop 1
	v_pk_mul_f32 v[72:73], v[128:129], v[112:113] op_sel_hi:[0,1]
	v_pk_mul_f32 v[68:69], v[128:129], v[68:69] op_sel_hi:[0,1]
	v_pk_mul_f32 v[74:75], v[128:129], v[114:115] op_sel_hi:[0,1]
	v_cvt_pk_bf16_f32 v72, v72, v73
	v_pk_mul_f32 v[70:71], v[128:129], v[70:71] op_sel_hi:[0,1]
	v_cvt_pk_bf16_f32 v68, v68, v69
	v_cvt_pk_bf16_f32 v73, v74, v75
	v_cvt_pk_bf16_f32 v69, v70, v71
	s_waitcnt lgkmcnt(0)
	s_nop 1
	v_permlane16_swap_b32 v72, v68
	v_permlane16_swap_b32 v73, v69
	v_mov_b32_e32 v70, v68
	v_mov_b32_e32 v68, v72
	v_mov_b32_e32 v71, v69
	v_mov_b32_e32 v69, v73
	v_or_b32_e32 v72, 32, v130
	v_ashrrev_i32_e32 v73, 31, v72
	v_lshlrev_b64 v[72:73], s7, v[72:73]
	v_lshl_add_u64 v[72:73], v[72:73], 1, v[84:85]
	global_store_dwordx4 v[72:73], v[68:71], off
	s_nop 1
	v_pk_mul_f32 v[68:69], v[128:129], v[104:105] op_sel_hi:[0,1]
	v_pk_mul_f32 v[64:65], v[128:129], v[64:65] op_sel_hi:[0,1]
	v_pk_mul_f32 v[70:71], v[128:129], v[106:107] op_sel_hi:[0,1]
	v_cvt_pk_bf16_f32 v68, v68, v69
	v_pk_mul_f32 v[66:67], v[128:129], v[66:67] op_sel_hi:[0,1]
	v_cvt_pk_bf16_f32 v64, v64, v65
	v_cvt_pk_bf16_f32 v69, v70, v71
	v_cvt_pk_bf16_f32 v65, v66, v67
	s_waitcnt lgkmcnt(0)
	s_nop 1
	v_permlane16_swap_b32 v68, v64
	v_permlane16_swap_b32 v69, v65
	v_mov_b32_e32 v66, v64
	v_mov_b32_e32 v64, v68
	v_mov_b32_e32 v67, v65
	v_mov_b32_e32 v65, v69
	v_or_b32_e32 v68, 48, v130
	v_ashrrev_i32_e32 v69, 31, v68
	v_lshlrev_b64 v[68:69], s7, v[68:69]
	v_lshl_add_u64 v[68:69], v[68:69], 1, v[84:85]
	global_store_dwordx4 v[68:69], v[64:67], off
	s_nop 1
	v_pk_mul_f32 v[64:65], v[128:129], v[116:117] op_sel_hi:[0,1]
	v_pk_mul_f32 v[66:67], v[128:129], v[118:119] op_sel_hi:[0,1]
	v_pk_mul_f32 v[56:57], v[128:129], v[56:57] op_sel_hi:[0,1]
	v_pk_mul_f32 v[58:59], v[128:129], v[58:59] op_sel_hi:[0,1]
	v_cvt_pk_bf16_f32 v64, v64, v65
	v_cvt_pk_bf16_f32 v65, v66, v67
	v_cvt_pk_bf16_f32 v56, v56, v57
	v_cvt_pk_bf16_f32 v57, v58, v59
	s_waitcnt lgkmcnt(0)
	s_nop 1
	v_permlane16_swap_b32 v65, v57
	v_permlane16_swap_b32 v64, v56
	v_mov_b32_e32 v59, v57
	v_mov_b32_e32 v57, v65
	v_mov_b32_e32 v58, v56
	v_mov_b32_e32 v56, v64
	global_store_dwordx4 v[86:87], v[56:59], off offset:256
	s_nop 1
	v_pk_mul_f32 v[56:57], v[128:129], v[108:109] op_sel_hi:[0,1]
	v_pk_mul_f32 v[58:59], v[128:129], v[110:111] op_sel_hi:[0,1]
	v_pk_mul_f32 v[48:49], v[128:129], v[48:49] op_sel_hi:[0,1]
	v_pk_mul_f32 v[50:51], v[128:129], v[50:51] op_sel_hi:[0,1]
	v_cvt_pk_bf16_f32 v56, v56, v57
	v_cvt_pk_bf16_f32 v57, v58, v59
	v_cvt_pk_bf16_f32 v48, v48, v49
	v_cvt_pk_bf16_f32 v49, v50, v51
	s_waitcnt lgkmcnt(0)
	s_nop 1
	v_permlane16_swap_b32 v57, v49
	v_permlane16_swap_b32 v56, v48
	v_mov_b32_e32 v51, v49
	v_mov_b32_e32 v49, v57
	v_mov_b32_e32 v50, v48
	v_mov_b32_e32 v48, v56
	global_store_dwordx4 v[120:121], v[48:51], off offset:256
	s_nop 1
	v_pk_mul_f32 v[48:49], v[128:129], v[100:101] op_sel_hi:[0,1]
	v_pk_mul_f32 v[50:51], v[128:129], v[102:103] op_sel_hi:[0,1]
	v_pk_mul_f32 v[44:45], v[128:129], v[44:45] op_sel_hi:[0,1]
	v_pk_mul_f32 v[46:47], v[128:129], v[46:47] op_sel_hi:[0,1]
	v_cvt_pk_bf16_f32 v48, v48, v49
	v_cvt_pk_bf16_f32 v49, v50, v51
	v_cvt_pk_bf16_f32 v44, v44, v45
	v_cvt_pk_bf16_f32 v45, v46, v47
	s_waitcnt lgkmcnt(0)
; __device__ __forceinline__ float sigm_f(float x) { return __builtin_amdgcn_rcpf(1.f + __builtin_amdgcn_exp2f(x * -1.4426950408889634f)); }
; __device__ __forceinline__ float silu_f(float x) { return x * sigm_f(x); }
; #define SCHED __builtin_amdgcn_sched_barrier(0)
; template <int ACT>
; __device__ __forceinline__ void epi_tok(f32x4 (&acc)[2][2][4][2], bf16* __restrict__ dst, int ld, int tok0, int colbase,
;                                         const float* __restrict__ bias, float scale) {
;     ...
;   _Pragma("unroll") for (int ai = 0; ai < 2; ++ai) _Pragma("unroll") for (int bj = 0; bj < 2; ++bj) _Pragma("unroll") for (int m = 0; m < 4; ++m) {
;     uint2 pk[2];
;     _Pragma("unroll") for (int n = 0; n < 2; ++n) {
;       f32x4 v = acc[ai][bj][m][n];
;       if (ACT == 0) { _Pragma("unroll") for (int j = 0; j < 4; ++j) v[j] = silu_f(v[j]); }
;       else if (ACT == 1) { float4 b = *(const float4*)(bias + colbase + bj * 128 + t.wc * 32 + n * 16 + t.fq * 4);
;         v[0] = sigm_f(v[0] + b.x); v[1] = sigm_f(v[1] + b.y); v[2] = sigm_f(v[2] + b.z); v[3] = sigm_f(v[3] + b.w); }
;       else { _Pragma("unroll") for (int j = 0; j < 4; ++j) v[j] *= scale; }
;       pk[n] = pack4(v[0], v[1], v[2], v[3]);
;     }
;     const uint2 snd = odd ? pk[0] : pk[1];
;     uint2 rcv;
;     rcv.x = (unsigned)__builtin_amdgcn_ds_bpermute(paddr, (int)snd.x);
;     rcv.y = (unsigned)__builtin_amdgcn_ds_bpermute(paddr, (int)snd.y);
;     const u32x4 outv = odd ? u32x4{rcv.x, rcv.y, pk[1].x, pk[1].y} : u32x4{pk[0].x, pk[0].y, rcv.x, rcv.y};
;     const int row = ai * 128 + t.wr * 64 + m * 16 + t.fr;
;     const int col = bj * 128 + t.wc * 32 + (odd ? 16 + (t.fq - 1) * 4 : t.fq * 4);
;     *(u32x4*)(dst + (size_t)(tok0 + row) * ld + colbase + col) = outv;
;     SCHED;
;   }
	s_nop 1
	v_permlane16_swap_b32 v49, v45
	v_permlane16_swap_b32 v48, v44
	v_mov_b32_e32 v47, v45
	v_mov_b32_e32 v45, v49
	v_mov_b32_e32 v46, v44
	v_mov_b32_e32 v44, v48
	global_store_dwordx4 v[72:73], v[44:47], off offset:256
	s_nop 1
	v_pk_mul_f32 v[44:45], v[128:129], v[96:97] op_sel_hi:[0,1]
	v_pk_mul_f32 v[46:47], v[128:129], v[98:99] op_sel_hi:[0,1]
	v_pk_mul_f32 v[36:37], v[128:129], v[36:37] op_sel_hi:[0,1]
	v_pk_mul_f32 v[38:39], v[128:129], v[38:39] op_sel_hi:[0,1]
	v_cvt_pk_bf16_f32 v44, v44, v45
	v_cvt_pk_bf16_f32 v45, v46, v47
	v_cvt_pk_bf16_f32 v36, v36, v37
	v_cvt_pk_bf16_f32 v37, v38, v39
	s_waitcnt lgkmcnt(0)
	s_nop 1
	v_permlane16_swap_b32 v45, v37
	v_permlane16_swap_b32 v44, v36
	v_mov_b32_e32 v39, v37
	v_mov_b32_e32 v37, v45
	v_mov_b32_e32 v38, v36
	v_mov_b32_e32 v36, v44
	global_store_dwordx4 v[68:69], v[36:39], off offset:256
	s_nop 1
	v_pk_mul_f32 v[36:37], v[128:129], v[92:93] op_sel_hi:[0,1]
	v_pk_mul_f32 v[32:33], v[128:129], v[32:33] op_sel_hi:[0,1]
	v_cvt_pk_bf16_f32 v37, v36, v37
	v_pk_mul_f32 v[34:35], v[128:129], v[34:35] op_sel_hi:[0,1]
	v_cvt_pk_bf16_f32 v32, v32, v33
	v_pk_mul_f32 v[38:39], v[128:129], v[94:95] op_sel_hi:[0,1]
	v_cvt_pk_bf16_f32 v33, v34, v35
	v_cvt_pk_bf16_f32 v38, v38, v39
	v_add_u32_e32 v36, 0x80, v130
	s_waitcnt lgkmcnt(0)
	s_nop 1
	v_permlane16_swap_b32 v37, v32
	v_permlane16_swap_b32 v38, v33
	v_mov_b32_e32 v34, v32
	v_mov_b32_e32 v32, v37
	v_mov_b32_e32 v35, v33
	v_mov_b32_e32 v33, v38
	v_ashrrev_i32_e32 v37, 31, v36
	v_lshlrev_b64 v[36:37], s7, v[36:37]
	v_lshl_add_u64 v[36:37], v[36:37], 1, v[84:85]
	global_store_dwordx4 v[36:37], v[32:35], off
	s_nop 1
	v_pk_mul_f32 v[32:33], v[128:129], v[88:89] op_sel_hi:[0,1]
	v_pk_mul_f32 v[28:29], v[128:129], v[28:29] op_sel_hi:[0,1]
	v_pk_mul_f32 v[34:35], v[128:129], v[90:91] op_sel_hi:[0,1]
	v_cvt_pk_bf16_f32 v32, v32, v33
	v_pk_mul_f32 v[30:31], v[128:129], v[30:31] op_sel_hi:[0,1]
	v_cvt_pk_bf16_f32 v28, v28, v29
	v_cvt_pk_bf16_f32 v33, v34, v35
	v_cvt_pk_bf16_f32 v29, v30, v31
	s_waitcnt lgkmcnt(0)
	s_nop 1
	v_permlane16_swap_b32 v32, v28
	v_permlane16_swap_b32 v33, v29
	v_mov_b32_e32 v30, v28
	v_mov_b32_e32 v28, v32
	v_mov_b32_e32 v31, v29
	v_mov_b32_e32 v29, v33
	v_add_u32_e32 v32, 0x90, v130
	v_ashrrev_i32_e32 v33, 31, v32
	v_lshlrev_b64 v[32:33], s7, v[32:33]
	v_lshl_add_u64 v[32:33], v[32:33], 1, v[84:85]
	global_store_dwordx4 v[32:33], v[28:31], off
	s_nop 1
	v_pk_mul_f32 v[28:29], v[128:129], v[76:77] op_sel_hi:[0,1]
	v_pk_mul_f32 v[24:25], v[128:129], v[24:25] op_sel_hi:[0,1]
	v_pk_mul_f32 v[30:31], v[128:129], v[78:79] op_sel_hi:[0,1]
	v_cvt_pk_bf16_f32 v28, v28, v29
	v_pk_mul_f32 v[26:27], v[128:129], v[26:27] op_sel_hi:[0,1]
	v_cvt_pk_bf16_f32 v24, v24, v25
	v_cvt_pk_bf16_f32 v29, v30, v31
	v_cvt_pk_bf16_f32 v25, v26, v27
	s_waitcnt lgkmcnt(0)
	s_nop 1
	v_permlane16_swap_b32 v28, v24
	v_permlane16_swap_b32 v29, v25
	v_mov_b32_e32 v26, v24
	v_mov_b32_e32 v24, v28
	v_mov_b32_e32 v27, v25
	v_mov_b32_e32 v25, v29
	v_add_u32_e32 v28, 0xa0, v130
	v_ashrrev_i32_e32 v29, 31, v28
	v_lshlrev_b64 v[28:29], s7, v[28:29]
	v_lshl_add_u64 v[28:29], v[28:29], 1, v[84:85]
	global_store_dwordx4 v[28:29], v[24:27], off
	s_nop 1
	v_pk_mul_f32 v[24:25], v[128:129], v[52:53] op_sel_hi:[0,1]
	v_pk_mul_f32 v[16:17], v[128:129], v[16:17] op_sel_hi:[0,1]
	v_pk_mul_f32 v[26:27], v[128:129], v[54:55] op_sel_hi:[0,1]
	v_cvt_pk_bf16_f32 v24, v24, v25
	v_pk_mul_f32 v[18:19], v[128:129], v[18:19] op_sel_hi:[0,1]
	v_cvt_pk_bf16_f32 v16, v16, v17
	v_cvt_pk_bf16_f32 v25, v26, v27
	v_cvt_pk_bf16_f32 v17, v18, v19
	s_waitcnt lgkmcnt(0)
	s_nop 1
	v_permlane16_swap_b32 v24, v16
	v_permlane16_swap_b32 v25, v17
	v_mov_b32_e32 v18, v16
	v_mov_b32_e32 v16, v24
	v_mov_b32_e32 v19, v17
	v_mov_b32_e32 v17, v25
	v_add_u32_e32 v24, 0xb0, v130
	v_ashrrev_i32_e32 v25, 31, v24
	v_lshlrev_b64 v[24:25], s7, v[24:25]
	v_lshl_add_u64 v[24:25], v[24:25], 1, v[84:85]
	global_store_dwordx4 v[24:25], v[16:19], off
	s_nop 1
	v_pk_mul_f32 v[16:17], v[128:129], v[80:81] op_sel_hi:[0,1]
	v_pk_mul_f32 v[18:19], v[128:129], v[82:83] op_sel_hi:[0,1]
	v_pk_mul_f32 v[12:13], v[128:129], v[12:13] op_sel_hi:[0,1]
	v_pk_mul_f32 v[14:15], v[128:129], v[14:15] op_sel_hi:[0,1]
	v_cvt_pk_bf16_f32 v16, v16, v17
	v_cvt_pk_bf16_f32 v17, v18, v19
	v_cvt_pk_bf16_f32 v12, v12, v13
	v_cvt_pk_bf16_f32 v13, v14, v15
	s_waitcnt lgkmcnt(0)
	s_nop 1
	v_permlane16_swap_b32 v17, v13
	v_permlane16_swap_b32 v16, v12
	v_mov_b32_e32 v15, v13
	v_mov_b32_e32 v13, v17
	v_mov_b32_e32 v14, v12
	v_mov_b32_e32 v12, v16
	global_store_dwordx4 v[36:37], v[12:15], off offset:256
	s_nop 1
	v_pk_mul_f32 v[12:13], v[128:129], v[60:61] op_sel_hi:[0,1]
	v_pk_mul_f32 v[14:15], v[128:129], v[62:63] op_sel_hi:[0,1]
	v_pk_mul_f32 v[8:9], v[128:129], v[8:9] op_sel_hi:[0,1]
	v_pk_mul_f32 v[10:11], v[128:129], v[10:11] op_sel_hi:[0,1]
	v_cvt_pk_bf16_f32 v12, v12, v13
	v_cvt_pk_bf16_f32 v13, v14, v15
	v_cvt_pk_bf16_f32 v8, v8, v9
	v_cvt_pk_bf16_f32 v9, v10, v11
	s_waitcnt lgkmcnt(0)
	s_nop 1
	v_permlane16_swap_b32 v13, v9
	v_permlane16_swap_b32 v12, v8
	v_mov_b32_e32 v11, v9
	v_mov_b32_e32 v9, v13
	v_mov_b32_e32 v10, v8
	v_mov_b32_e32 v8, v12
	global_store_dwordx4 v[32:33], v[8:11], off offset:256
	s_nop 1
	v_pk_mul_f32 v[8:9], v[128:129], v[40:41] op_sel_hi:[0,1]
	v_pk_mul_f32 v[10:11], v[128:129], v[42:43] op_sel_hi:[0,1]
	v_pk_mul_f32 v[4:5], v[128:129], v[4:5] op_sel_hi:[0,1]
	v_pk_mul_f32 v[6:7], v[128:129], v[6:7] op_sel_hi:[0,1]
	v_cvt_pk_bf16_f32 v8, v8, v9
	v_cvt_pk_bf16_f32 v9, v10, v11
	v_cvt_pk_bf16_f32 v4, v4, v5
	v_cvt_pk_bf16_f32 v5, v6, v7
	s_waitcnt lgkmcnt(0)
	s_nop 1
	v_permlane16_swap_b32 v9, v5
	v_permlane16_swap_b32 v8, v4
	v_mov_b32_e32 v7, v5
	v_mov_b32_e32 v5, v9
	v_mov_b32_e32 v6, v4
	v_mov_b32_e32 v4, v8
	global_store_dwordx4 v[28:29], v[4:7], off offset:256
	s_nop 1
	v_pk_mul_f32 v[4:5], v[128:129], v[20:21] op_sel_hi:[0,1]
	v_pk_mul_f32 v[6:7], v[128:129], v[22:23] op_sel_hi:[0,1]
	v_pk_mul_f32 v[0:1], v[128:129], v[0:1] op_sel_hi:[0,1]
	v_pk_mul_f32 v[2:3], v[128:129], v[2:3] op_sel_hi:[0,1]
	v_cvt_pk_bf16_f32 v4, v4, v5
	v_cvt_pk_bf16_f32 v5, v6, v7
	v_cvt_pk_bf16_f32 v0, v0, v1
	v_cvt_pk_bf16_f32 v1, v2, v3
	s_waitcnt lgkmcnt(0)
	s_nop 1
	v_permlane16_swap_b32 v5, v1
	v_permlane16_swap_b32 v4, v0
	v_mov_b32_e32 v3, v1
	v_mov_b32_e32 v1, v5
	v_mov_b32_e32 v2, v0
	v_mov_b32_e32 v0, v4
	global_store_dwordx4 v[24:25], v[0:3], off offset:256
	s_mov_b64 s[14:15], -1
	s_and_b64 vcc, exec, s[0:1]
	s_cbranch_vccnz .LBB0_534
